# v72 + row-max head trim (v70's edit): all branch-chain trims combined
# speedup vs baseline: 1.0054x; 1.0017x over previous
; template <int DQK, int KROW, bool BIAS, bool MAPS2>
; DI void attn_core(const int t, const u16* __restrict__ Q, int ldq, const u16* __restrict__ Kp, int ldk, const u16* __restrict__ Vt, int q0,
;                   char* lds, const float* lut, float b31, f32x16 (&o)[4], float& l_out) {
;     ...
;       float mx = s[0][0];
; #pragma unroll
;       for (int k2 = 0; k2 < 2; ++k2)
; #pragma unroll
;         for (int i = 0; i < 16; ++i) mx = fmaxf(mx, s[k2][i]);
;       mx = xhalf_max(mx);
;       if (__builtin_amdgcn_ballot_w64(kt == 0 || mx > RESCALE_THR)) {
;         const float delta = (kt == 0) ? mx : fmaxf(mx, 0.f);
;         const float alpha = __builtin_amdgcn_exp2f(-delta);
;         m_run += delta;
;         l_run *= alpha;
; #pragma unroll
;         for (int dt = 0; dt < 4; ++dt)
; #pragma unroll
;           for (int i = 0; i < 16; ++i) o[dt][i] *= alpha;
; #pragma unroll
;         for (int k2 = 0; k2 < 2; ++k2)
; #pragma unroll
;           for (int i = 0; i < 16; ++i) s[k2][i] -= delta;
;       }
;       float ps = 0.f;
; #pragma unroll
;       for (int k2 = 0; k2 < 2; ++k2)
; #pragma unroll
;         for (int i = 0; i < 16; ++i) { const float pv = __builtin_amdgcn_exp2f(s[k2][i]); s[k2][i] = pv; ps += pv; }
;       l_run += ps;
.LBB0_238:
	s_or_b64 exec, exec, s[0:1]
	s_nop 4
	s_nop 0
	v_max_f32_e32 v0, v96, v97
	v_max3_f32 v0, v0, v98, v99
	v_max3_f32 v0, v0, v100, v101
	v_max3_f32 v0, v0, v102, v103
	v_max3_f32 v0, v0, v104, v105
	v_max3_f32 v0, v0, v106, v107
	v_max3_f32 v0, v0, v108, v109
	v_max3_f32 v0, v0, v110, v111
	v_max3_f32 v0, v0, v80, v81
	v_max3_f32 v0, v0, v82, v83
	v_max3_f32 v0, v0, v84, v85
	v_max3_f32 v0, v0, v86, v87
	v_max3_f32 v0, v0, v88, v89
	v_max3_f32 v0, v0, v90, v91
	v_max3_f32 v0, v0, v92, v93
	v_max3_f32 v0, v0, v94, v95
	v_mov_b32_e32 v2, v0
	s_nop 1
	v_permlane32_swap_b32_e32 v0, v2
	v_max_f32_e32 v0, v0, v2
	v_cmp_lt_f32_e32 vcc, s97, v0
	s_cbranch_vccz .LBB0_242
	s_cmp_eq_u32 s96, 0
	s_cselect_b64 s[0:1], -1, 0
	v_max_f32_e32 v2, v0, v0
	v_max_f32_e32 v2, 0, v2
	v_cndmask_b32_e64 v0, v2, v0, s[0:1]
	v_exp_f32_e64 v2, -v0
	v_add_f32_e32 v161, v161, v0
	v_pk_add_f32 v[96:97], v[96:97], v[0:1] op_sel_hi:[1,0] neg_lo:[0,1] neg_hi:[0,1]
	v_pk_add_f32 v[98:99], v[98:99], v[0:1] op_sel_hi:[1,0] neg_lo:[0,1] neg_hi:[0,1]
	v_pk_mul_f32 v[78:79], v[78:79], v[2:3] op_sel_hi:[1,0]
	v_pk_mul_f32 v[76:77], v[76:77], v[2:3] op_sel_hi:[1,0]
	v_pk_mul_f32 v[74:75], v[74:75], v[2:3] op_sel_hi:[1,0]
	v_pk_mul_f32 v[72:73], v[72:73], v[2:3] op_sel_hi:[1,0]
	v_pk_mul_f32 v[70:71], v[70:71], v[2:3] op_sel_hi:[1,0]
	v_pk_mul_f32 v[68:69], v[68:69], v[2:3] op_sel_hi:[1,0]
	v_pk_mul_f32 v[66:67], v[66:67], v[2:3] op_sel_hi:[1,0]
	v_pk_mul_f32 v[64:65], v[64:65], v[2:3] op_sel_hi:[1,0]
	v_pk_mul_f32 v[62:63], v[62:63], v[2:3] op_sel_hi:[1,0]
	v_pk_mul_f32 v[60:61], v[60:61], v[2:3] op_sel_hi:[1,0]
	v_pk_mul_f32 v[58:59], v[58:59], v[2:3] op_sel_hi:[1,0]
	v_pk_mul_f32 v[56:57], v[56:57], v[2:3] op_sel_hi:[1,0]
	v_pk_mul_f32 v[54:55], v[54:55], v[2:3] op_sel_hi:[1,0]
	v_pk_mul_f32 v[52:53], v[52:53], v[2:3] op_sel_hi:[1,0]
	v_pk_mul_f32 v[50:51], v[50:51], v[2:3] op_sel_hi:[1,0]
	v_pk_mul_f32 v[48:49], v[48:49], v[2:3] op_sel_hi:[1,0]
	v_pk_mul_f32 v[46:47], v[46:47], v[2:3] op_sel_hi:[1,0]
	v_pk_mul_f32 v[44:45], v[44:45], v[2:3] op_sel_hi:[1,0]
	v_pk_mul_f32 v[42:43], v[42:43], v[2:3] op_sel_hi:[1,0]
	v_pk_mul_f32 v[40:41], v[40:41], v[2:3] op_sel_hi:[1,0]
	v_pk_mul_f32 v[38:39], v[38:39], v[2:3] op_sel_hi:[1,0]
	v_pk_mul_f32 v[36:37], v[36:37], v[2:3] op_sel_hi:[1,0]
	v_pk_mul_f32 v[34:35], v[34:35], v[2:3] op_sel_hi:[1,0]
	v_pk_mul_f32 v[32:33], v[32:33], v[2:3] op_sel_hi:[1,0]
	v_pk_mul_f32 v[30:31], v[30:31], v[2:3] op_sel_hi:[1,0]
	v_pk_mul_f32 v[28:29], v[28:29], v[2:3] op_sel_hi:[1,0]
	v_pk_mul_f32 v[26:27], v[26:27], v[2:3] op_sel_hi:[1,0]
	v_pk_mul_f32 v[24:25], v[24:25], v[2:3] op_sel_hi:[1,0]
	v_pk_mul_f32 v[22:23], v[22:23], v[2:3] op_sel_hi:[1,0]
	v_pk_mul_f32 v[20:21], v[20:21], v[2:3] op_sel_hi:[1,0]
	v_pk_mul_f32 v[18:19], v[18:19], v[2:3] op_sel_hi:[1,0]
	v_pk_mul_f32 v[16:17], v[16:17], v[2:3] op_sel_hi:[1,0]
	v_pk_add_f32 v[100:101], v[100:101], v[0:1] op_sel_hi:[1,0] neg_lo:[0,1] neg_hi:[0,1]
	v_pk_add_f32 v[102:103], v[102:103], v[0:1] op_sel_hi:[1,0] neg_lo:[0,1] neg_hi:[0,1]
	v_pk_add_f32 v[104:105], v[104:105], v[0:1] op_sel_hi:[1,0] neg_lo:[0,1] neg_hi:[0,1]
	v_pk_add_f32 v[106:107], v[106:107], v[0:1] op_sel_hi:[1,0] neg_lo:[0,1] neg_hi:[0,1]
	v_pk_add_f32 v[108:109], v[108:109], v[0:1] op_sel_hi:[1,0] neg_lo:[0,1] neg_hi:[0,1]
	v_pk_add_f32 v[110:111], v[110:111], v[0:1] op_sel_hi:[1,0] neg_lo:[0,1] neg_hi:[0,1]
	v_pk_add_f32 v[80:81], v[80:81], v[0:1] op_sel_hi:[1,0] neg_lo:[0,1] neg_hi:[0,1]
	v_pk_add_f32 v[82:83], v[82:83], v[0:1] op_sel_hi:[1,0] neg_lo:[0,1] neg_hi:[0,1]
	v_pk_add_f32 v[84:85], v[84:85], v[0:1] op_sel_hi:[1,0] neg_lo:[0,1] neg_hi:[0,1]
	v_pk_add_f32 v[86:87], v[86:87], v[0:1] op_sel_hi:[1,0] neg_lo:[0,1] neg_hi:[0,1]
	v_pk_add_f32 v[88:89], v[88:89], v[0:1] op_sel_hi:[1,0] neg_lo:[0,1] neg_hi:[0,1]
	v_pk_add_f32 v[90:91], v[90:91], v[0:1] op_sel_hi:[1,0] neg_lo:[0,1] neg_hi:[0,1]
	v_pk_add_f32 v[92:93], v[92:93], v[0:1] op_sel_hi:[1,0] neg_lo:[0,1] neg_hi:[0,1]
	v_pk_add_f32 v[94:95], v[94:95], v[0:1] op_sel_hi:[1,0] neg_lo:[0,1] neg_hi:[0,1]
	v_mul_f32_e32 v151, v151, v2

; template <int DQK, int KROW, bool BIAS, bool MAPS2>
; DI void attn_core(const int t, const u16* __restrict__ Q, int ldq, const u16* __restrict__ Kp, int ldk, const u16* __restrict__ Vt, int q0,
;                   char* lds, const float* lut, float b31, f32x16 (&o)[4], float& l_out) {
;     ...
;       float mx = s[0][0];
; #pragma unroll
;       for (int k2 = 0; k2 < 2; ++k2)
; #pragma unroll
;         for (int i = 0; i < 16; ++i) mx = fmaxf(mx, s[k2][i]);
;       mx = xhalf_max(mx);
;       if (__builtin_amdgcn_ballot_w64(kt == 0 || mx > RESCALE_THR)) {
;         const float delta = (kt == 0) ? mx : fmaxf(mx, 0.f);
;         const float alpha = __builtin_amdgcn_exp2f(-delta);
;         m_run += delta;
;         l_run *= alpha;
; #pragma unroll
;         for (int dt = 0; dt < 4; ++dt)
; #pragma unroll
;           for (int i = 0; i < 16; ++i) o[dt][i] *= alpha;
; #pragma unroll
;         for (int k2 = 0; k2 < 2; ++k2)
; #pragma unroll
;           for (int i = 0; i < 16; ++i) s[k2][i] -= delta;
;       }
;       float ps = 0.f;
; #pragma unroll
;       for (int k2 = 0; k2 < 2; ++k2)
; #pragma unroll
;         for (int i = 0; i < 16; ++i) { const float pv = __builtin_amdgcn_exp2f(s[k2][i]); s[k2][i] = pv; ps += pv; }
;       l_run += ps;
.LBB0_259:
	s_or_b64 exec, exec, s[0:1]
	s_nop 3
	v_max_f32_e32 v181, v82, v83
	v_max3_f32 v181, v181, v84, v85
	v_max3_f32 v181, v181, v86, v87
	v_max3_f32 v181, v181, v88, v89
	v_max3_f32 v181, v181, v90, v91
	v_max3_f32 v181, v181, v92, v93
	v_max3_f32 v181, v181, v94, v95
	v_max3_f32 v181, v181, v96, v97
	v_max3_f32 v181, v181, v66, v67
	v_max3_f32 v181, v181, v68, v69
	v_max3_f32 v181, v181, v70, v71
	v_max3_f32 v181, v181, v72, v73
	v_max3_f32 v181, v181, v74, v75
	v_max3_f32 v181, v181, v76, v77
	v_max3_f32 v181, v181, v78, v79
	v_max3_f32 v181, v181, v80, v81
	v_mov_b32_e32 v182, v181
	s_nop 1
	v_permlane32_swap_b32_e32 v181, v182
	v_max_f32_e32 v181, v181, v182
	v_cmp_lt_f32_e32 vcc, s97, v181
	s_cbranch_vccz .LBB0_261
	s_cmp_eq_u32 s93, 0
	s_cselect_b64 s[0:1], -1, 0
	v_max_f32_e32 v182, v181, v181
	v_max_f32_e32 v182, 0, v182
	v_cndmask_b32_e64 v182, v182, v181, s[0:1]
	v_exp_f32_e64 v184, -v182
	v_add_f32_e32 v180, v180, v182
	v_pk_add_f32 v[82:83], v[82:83], v[182:183] op_sel_hi:[1,0] neg_lo:[0,1] neg_hi:[0,1]
	v_pk_add_f32 v[84:85], v[84:85], v[182:183] op_sel_hi:[1,0] neg_lo:[0,1] neg_hi:[0,1]
	v_pk_mul_f32 v[64:65], v[64:65], v[184:185] op_sel_hi:[1,0]
	v_pk_mul_f32 v[62:63], v[62:63], v[184:185] op_sel_hi:[1,0]
	v_pk_mul_f32 v[60:61], v[60:61], v[184:185] op_sel_hi:[1,0]
	v_pk_mul_f32 v[58:59], v[58:59], v[184:185] op_sel_hi:[1,0]
	v_pk_mul_f32 v[56:57], v[56:57], v[184:185] op_sel_hi:[1,0]
	v_pk_mul_f32 v[54:55], v[54:55], v[184:185] op_sel_hi:[1,0]
	v_pk_mul_f32 v[52:53], v[52:53], v[184:185] op_sel_hi:[1,0]
	v_pk_mul_f32 v[50:51], v[50:51], v[184:185] op_sel_hi:[1,0]
	v_pk_mul_f32 v[48:49], v[48:49], v[184:185] op_sel_hi:[1,0]
	v_pk_mul_f32 v[46:47], v[46:47], v[184:185] op_sel_hi:[1,0]
	v_pk_mul_f32 v[44:45], v[44:45], v[184:185] op_sel_hi:[1,0]
	v_pk_mul_f32 v[42:43], v[42:43], v[184:185] op_sel_hi:[1,0]
	v_pk_mul_f32 v[40:41], v[40:41], v[184:185] op_sel_hi:[1,0]
	v_pk_mul_f32 v[38:39], v[38:39], v[184:185] op_sel_hi:[1,0]
	v_pk_mul_f32 v[36:37], v[36:37], v[184:185] op_sel_hi:[1,0]
	v_pk_mul_f32 v[34:35], v[34:35], v[184:185] op_sel_hi:[1,0]
	v_pk_mul_f32 v[32:33], v[32:33], v[184:185] op_sel_hi:[1,0]
	v_pk_mul_f32 v[30:31], v[30:31], v[184:185] op_sel_hi:[1,0]
	v_pk_mul_f32 v[28:29], v[28:29], v[184:185] op_sel_hi:[1,0]
	v_pk_mul_f32 v[26:27], v[26:27], v[184:185] op_sel_hi:[1,0]
	v_pk_mul_f32 v[24:25], v[24:25], v[184:185] op_sel_hi:[1,0]
	v_pk_mul_f32 v[22:23], v[22:23], v[184:185] op_sel_hi:[1,0]
	v_pk_mul_f32 v[20:21], v[20:21], v[184:185] op_sel_hi:[1,0]
	v_pk_mul_f32 v[18:19], v[18:19], v[184:185] op_sel_hi:[1,0]
	v_pk_mul_f32 v[16:17], v[16:17], v[184:185] op_sel_hi:[1,0]
	v_pk_mul_f32 v[14:15], v[14:15], v[184:185] op_sel_hi:[1,0]
	v_pk_mul_f32 v[12:13], v[12:13], v[184:185] op_sel_hi:[1,0]
	v_pk_mul_f32 v[10:11], v[10:11], v[184:185] op_sel_hi:[1,0]
	v_pk_mul_f32 v[8:9], v[8:9], v[184:185] op_sel_hi:[1,0]
	v_pk_mul_f32 v[6:7], v[6:7], v[184:185] op_sel_hi:[1,0]
	v_pk_mul_f32 v[4:5], v[4:5], v[184:185] op_sel_hi:[1,0]
	v_pk_mul_f32 v[2:3], v[2:3], v[184:185] op_sel_hi:[1,0]
	v_pk_add_f32 v[86:87], v[86:87], v[182:183] op_sel_hi:[1,0] neg_lo:[0,1] neg_hi:[0,1]
	v_pk_add_f32 v[88:89], v[88:89], v[182:183] op_sel_hi:[1,0] neg_lo:[0,1] neg_hi:[0,1]
	v_pk_add_f32 v[90:91], v[90:91], v[182:183] op_sel_hi:[1,0] neg_lo:[0,1] neg_hi:[0,1]
	v_pk_add_f32 v[92:93], v[92:93], v[182:183] op_sel_hi:[1,0] neg_lo:[0,1] neg_hi:[0,1]
	v_pk_add_f32 v[94:95], v[94:95], v[182:183] op_sel_hi:[1,0] neg_lo:[0,1] neg_hi:[0,1]
	v_pk_add_f32 v[96:97], v[96:97], v[182:183] op_sel_hi:[1,0] neg_lo:[0,1] neg_hi:[0,1]
	v_pk_add_f32 v[66:67], v[66:67], v[182:183] op_sel_hi:[1,0] neg_lo:[0,1] neg_hi:[0,1]
	v_pk_add_f32 v[68:69], v[68:69], v[182:183] op_sel_hi:[1,0] neg_lo:[0,1] neg_hi:[0,1]
	v_pk_add_f32 v[70:71], v[70:71], v[182:183] op_sel_hi:[1,0] neg_lo:[0,1] neg_hi:[0,1]
	v_pk_add_f32 v[72:73], v[72:73], v[182:183] op_sel_hi:[1,0] neg_lo:[0,1] neg_hi:[0,1]
	v_pk_add_f32 v[74:75], v[74:75], v[182:183] op_sel_hi:[1,0] neg_lo:[0,1] neg_hi:[0,1]
	v_pk_add_f32 v[76:77], v[76:77], v[182:183] op_sel_hi:[1,0] neg_lo:[0,1] neg_hi:[0,1]
	v_pk_add_f32 v[78:79], v[78:79], v[182:183] op_sel_hi:[1,0] neg_lo:[0,1] neg_hi:[0,1]
	v_pk_add_f32 v[80:81], v[80:81], v[182:183] op_sel_hi:[1,0] neg_lo:[0,1] neg_hi:[0,1]
	v_mul_f32_e32 v0, v0, v184

; template <int DQK, int KROW, bool BIAS, bool MAPS2>
; DI void attn_core(const int t, const u16* __restrict__ Q, int ldq, const u16* __restrict__ Kp, int ldk, const u16* __restrict__ Vt, int q0,
;                   char* lds, const float* lut, float b31, f32x16 (&o)[4], float& l_out) {
;     ...
;       float mx = s[0][0];
; #pragma unroll
;       for (int k2 = 0; k2 < 2; ++k2)
; #pragma unroll
;         for (int i = 0; i < 16; ++i) mx = fmaxf(mx, s[k2][i]);
;       mx = xhalf_max(mx);
;       if (__builtin_amdgcn_ballot_w64(kt == 0 || mx > RESCALE_THR)) {
;         const float delta = (kt == 0) ? mx : fmaxf(mx, 0.f);
;         const float alpha = __builtin_amdgcn_exp2f(-delta);
;         m_run += delta;
;         l_run *= alpha;
; #pragma unroll
;         for (int dt = 0; dt < 4; ++dt)
; #pragma unroll
;           for (int i = 0; i < 16; ++i) o[dt][i] *= alpha;
; #pragma unroll
;         for (int k2 = 0; k2 < 2; ++k2)
; #pragma unroll
;           for (int i = 0; i < 16; ++i) s[k2][i] -= delta;
;       }
;       float ps = 0.f;
; #pragma unroll
;       for (int k2 = 0; k2 < 2; ++k2)
; #pragma unroll
;         for (int i = 0; i < 16; ++i) { const float pv = __builtin_amdgcn_exp2f(s[k2][i]); s[k2][i] = pv; ps += pv; }
;       l_run += ps;
.LBB0_273:
	s_or_b64 exec, exec, s[0:1]
	s_nop 3
	v_max_f32_e32 v181, v82, v83
	v_max3_f32 v181, v181, v84, v85
	v_max3_f32 v181, v181, v86, v87
	v_max3_f32 v181, v181, v88, v89
	v_max3_f32 v181, v181, v90, v91
	v_max3_f32 v181, v181, v92, v93
	v_max3_f32 v181, v181, v94, v95
	v_max3_f32 v181, v181, v96, v97
	v_max3_f32 v181, v181, v66, v67
	v_max3_f32 v181, v181, v68, v69
	v_max3_f32 v181, v181, v70, v71
	v_max3_f32 v181, v181, v72, v73
	v_max3_f32 v181, v181, v74, v75
	v_max3_f32 v181, v181, v76, v77
	v_max3_f32 v181, v181, v78, v79
	v_max3_f32 v181, v181, v80, v81
	v_mov_b32_e32 v182, v181
	s_nop 1
	v_permlane32_swap_b32_e32 v181, v182
	v_max_f32_e32 v181, v181, v182
	v_cmp_lt_f32_e32 vcc, s97, v181
	s_cbranch_vccz .LBB0_275
	s_cmp_eq_u32 s63, 0
	s_cselect_b64 s[0:1], -1, 0
	v_max_f32_e32 v182, v181, v181
	v_max_f32_e32 v182, 0, v182
	v_cndmask_b32_e64 v182, v182, v181, s[0:1]
	v_exp_f32_e64 v184, -v182
	v_add_f32_e32 v180, v180, v182
	v_pk_add_f32 v[82:83], v[82:83], v[182:183] op_sel_hi:[1,0] neg_lo:[0,1] neg_hi:[0,1]
	v_pk_add_f32 v[84:85], v[84:85], v[182:183] op_sel_hi:[1,0] neg_lo:[0,1] neg_hi:[0,1]
	v_pk_mul_f32 v[64:65], v[64:65], v[184:185] op_sel_hi:[1,0]
	v_pk_mul_f32 v[62:63], v[62:63], v[184:185] op_sel_hi:[1,0]
	v_pk_mul_f32 v[60:61], v[60:61], v[184:185] op_sel_hi:[1,0]
	v_pk_mul_f32 v[58:59], v[58:59], v[184:185] op_sel_hi:[1,0]
	v_pk_mul_f32 v[56:57], v[56:57], v[184:185] op_sel_hi:[1,0]
	v_pk_mul_f32 v[54:55], v[54:55], v[184:185] op_sel_hi:[1,0]
	v_pk_mul_f32 v[52:53], v[52:53], v[184:185] op_sel_hi:[1,0]
	v_pk_mul_f32 v[50:51], v[50:51], v[184:185] op_sel_hi:[1,0]
	v_pk_mul_f32 v[48:49], v[48:49], v[184:185] op_sel_hi:[1,0]
	v_pk_mul_f32 v[46:47], v[46:47], v[184:185] op_sel_hi:[1,0]
	v_pk_mul_f32 v[44:45], v[44:45], v[184:185] op_sel_hi:[1,0]
	v_pk_mul_f32 v[42:43], v[42:43], v[184:185] op_sel_hi:[1,0]
	v_pk_mul_f32 v[40:41], v[40:41], v[184:185] op_sel_hi:[1,0]
	v_pk_mul_f32 v[38:39], v[38:39], v[184:185] op_sel_hi:[1,0]
	v_pk_mul_f32 v[36:37], v[36:37], v[184:185] op_sel_hi:[1,0]
	v_pk_mul_f32 v[34:35], v[34:35], v[184:185] op_sel_hi:[1,0]
	v_pk_mul_f32 v[32:33], v[32:33], v[184:185] op_sel_hi:[1,0]
	v_pk_mul_f32 v[30:31], v[30:31], v[184:185] op_sel_hi:[1,0]
	v_pk_mul_f32 v[28:29], v[28:29], v[184:185] op_sel_hi:[1,0]
	v_pk_mul_f32 v[26:27], v[26:27], v[184:185] op_sel_hi:[1,0]
	v_pk_mul_f32 v[24:25], v[24:25], v[184:185] op_sel_hi:[1,0]
	v_pk_mul_f32 v[22:23], v[22:23], v[184:185] op_sel_hi:[1,0]
	v_pk_mul_f32 v[20:21], v[20:21], v[184:185] op_sel_hi:[1,0]
	v_pk_mul_f32 v[18:19], v[18:19], v[184:185] op_sel_hi:[1,0]
	v_pk_mul_f32 v[16:17], v[16:17], v[184:185] op_sel_hi:[1,0]
	v_pk_mul_f32 v[14:15], v[14:15], v[184:185] op_sel_hi:[1,0]
	v_pk_mul_f32 v[12:13], v[12:13], v[184:185] op_sel_hi:[1,0]
	v_pk_mul_f32 v[10:11], v[10:11], v[184:185] op_sel_hi:[1,0]
	v_pk_mul_f32 v[8:9], v[8:9], v[184:185] op_sel_hi:[1,0]
	v_pk_mul_f32 v[6:7], v[6:7], v[184:185] op_sel_hi:[1,0]
	v_pk_mul_f32 v[4:5], v[4:5], v[184:185] op_sel_hi:[1,0]
	v_pk_mul_f32 v[2:3], v[2:3], v[184:185] op_sel_hi:[1,0]
	v_pk_add_f32 v[86:87], v[86:87], v[182:183] op_sel_hi:[1,0] neg_lo:[0,1] neg_hi:[0,1]
	v_pk_add_f32 v[88:89], v[88:89], v[182:183] op_sel_hi:[1,0] neg_lo:[0,1] neg_hi:[0,1]
	v_pk_add_f32 v[90:91], v[90:91], v[182:183] op_sel_hi:[1,0] neg_lo:[0,1] neg_hi:[0,1]
	v_pk_add_f32 v[92:93], v[92:93], v[182:183] op_sel_hi:[1,0] neg_lo:[0,1] neg_hi:[0,1]
	v_pk_add_f32 v[94:95], v[94:95], v[182:183] op_sel_hi:[1,0] neg_lo:[0,1] neg_hi:[0,1]
	v_pk_add_f32 v[96:97], v[96:97], v[182:183] op_sel_hi:[1,0] neg_lo:[0,1] neg_hi:[0,1]
	v_pk_add_f32 v[66:67], v[66:67], v[182:183] op_sel_hi:[1,0] neg_lo:[0,1] neg_hi:[0,1]
	v_pk_add_f32 v[68:69], v[68:69], v[182:183] op_sel_hi:[1,0] neg_lo:[0,1] neg_hi:[0,1]
	v_pk_add_f32 v[70:71], v[70:71], v[182:183] op_sel_hi:[1,0] neg_lo:[0,1] neg_hi:[0,1]
	v_pk_add_f32 v[72:73], v[72:73], v[182:183] op_sel_hi:[1,0] neg_lo:[0,1] neg_hi:[0,1]
	v_pk_add_f32 v[74:75], v[74:75], v[182:183] op_sel_hi:[1,0] neg_lo:[0,1] neg_hi:[0,1]
	v_pk_add_f32 v[76:77], v[76:77], v[182:183] op_sel_hi:[1,0] neg_lo:[0,1] neg_hi:[0,1]
	v_pk_add_f32 v[78:79], v[78:79], v[182:183] op_sel_hi:[1,0] neg_lo:[0,1] neg_hi:[0,1]
	v_pk_add_f32 v[80:81], v[80:81], v[182:183] op_sel_hi:[1,0] neg_lo:[0,1] neg_hi:[0,1]
	v_mul_f32_e32 v0, v0, v184
